# v20 + weight-tile loaders (W_gu, W_in): LDS-guard s_barrier moved from before the global loads to just before the ds_writes so loads issue without waiting on the slowest wave
# speedup vs baseline: 1.0303x; 1.0014x over previous
; #define LAS __attribute__((address_space(3)))
; __device__ __forceinline__ int otid() { int t = threadIdx.x; asm volatile("" : "+v"(t)); return t; }
; __device__ __forceinline__ unsigned pk2(float lo, float hi) { f32x2 f = {lo, hi}; bf16x2_t v = __builtin_convertvector(f, bf16x2_t); return __builtin_bit_cast(unsigned, v); }
; __device__ __forceinline__ void wtile(LAS float* tile, const float* src, int lds_src, const float* gain, bf16_t* dst, int K, int n0, int k0, int c0, int nvalid) {
;     const int tid = otid();
;     __syncthreads();
; #pragma unroll
;     for (int i = 0; i < 8; ++i) {
;         const int kk = (tid >> 6) + 8 * i, c = tid & 63;
;         float v = 0.f;
;         if (c0 + c < nvalid) { v = src[(size_t)(k0 + kk) * lds_src + c0 + c]; if (gain) v *= gain[k0 + kk]; }
;         tile[kk * 65 + c] = v;
;     }
;     __syncthreads();
;     const int n = tid >> 3, kc = (tid & 7) * 8;
;     float f[8];
; #pragma unroll
;     for (int j = 0; j < 8; ++j) f[j] = tile[(kc + j) * 65 + n];
;     u32x4 w; w.x = pk2(f[0], f[1]); w.y = pk2(f[2], f[3]); w.z = pk2(f[4], f[5]); w.w = pk2(f[6], f[7]);
;     *(u32x4*)(dst + (size_t)(n0 + n) * K + k0 + kc) = w;
; __device__ __forceinline__ void phase_weights(LAS unsigned char* lds, const Params& P) {
;     ...
;         } else if ((r -= T_OUT) < T_GU) { const int nb = r / 16, kb = r % 16;
;             const int j = nb >> 2, qd = nb & 3; const float* src = (qd < 2 ? P.in[26] : P.in[27]) + (size_t)l * DM * DFF;
;             wtile(tile, src, DFF, P.in[25] + l * DM, (bf16_t*)(ws + WS_WGU) + (size_t)l * 2 * DFF * DM, DM, nb * 64, kb * 64, j * 128 + (qd & 1) * 64, DFF);
.LBB0_27:
	s_andn2_b64 vcc, exec, s[0:1]
	s_cbranch_vccnz .LBB0_45
	s_add_i32 s16, s4, 0xfffffb80
	s_bitcmp0_b32 s4, 5
	s_cselect_b32 s1, s84, s86
	s_cselect_b32 s0, s85, s87
	s_add_u32 s27, s1, s24
	s_addc_u32 s30, s0, s5
	s_lshl_b32 s0, s18, 10
	s_ashr_i32 s1, s0, 31
	s_lshl_b64 s[0:1], s[0:1], 2
	s_add_u32 s28, s82, s0
	s_addc_u32 s29, s83, s1
	s_lshl_b32 s0, s4, 6
	s_lshl_b32 s26, s16, 2
	s_and_b32 s25, s0, 0x3c0
	s_lshl_b32 s0, s16, 1
	s_and_b32 s0, s0, 0x7fffff80
	s_and_b32 s1, s26, 64
	s_or_b32 s16, s0, s1
	v_mov_b32_e32 v10, v203
	s_lshl_b64 s[0:1], s[16:17], 2
	s_add_u32 s0, s27, s0
	v_and_b32_e32 v12, 63, v10
	v_ashrrev_i32_e32 v11, 6, v10
	s_addc_u32 s1, s30, s1
	v_lshlrev_b32_e32 v6, 2, v12
	v_lshl_add_u64 v[2:3], s[0:1], 0, v[6:7]
	v_add_u32_e32 v4, s25, v11
	v_mad_i64_i32 v[8:9], s[0:1], v4, s42, v[2:3]
	global_load_dword v6, v[8:9], off
	v_add_u32_e32 v5, 8, v4
	v_mad_i64_i32 v[14:15], s[0:1], v5, s42, v[2:3]
	global_load_dword v13, v[14:15], off
	v_add_u32_e32 v5, 16, v4
	v_mad_i64_i32 v[24:25], s[0:1], v5, s42, v[2:3]
	global_load_dword v16, v[24:25], off
	v_add_u32_e32 v5, 24, v4
	v_mad_i64_i32 v[14:15], s[0:1], v5, s42, v[2:3]
	global_load_dword v17, v[14:15], off
	v_add_u32_e32 v5, 32, v4
	v_mad_i64_i32 v[24:25], s[0:1], v5, s42, v[2:3]
	global_load_dword v18, v[24:25], off
	v_add_u32_e32 v5, 40, v4
	v_mad_i64_i32 v[14:15], s[0:1], v5, s42, v[2:3]
	global_load_dword v19, v[14:15], off
	v_add_u32_e32 v5, 48, v4
	v_mad_i64_i32 v[24:25], s[0:1], v5, s42, v[2:3]
	global_load_dword v20, v[24:25], off
	v_add_u32_e32 v5, 56, v4
	v_mad_i64_i32 v[14:15], s[0:1], v5, s42, v[2:3]
	global_load_dword v21, v[14:15], off
	v_lshl_add_u32 v5, v12, 2, 0
	v_mul_lo_u32 v11, v11, s40
	v_add_u32_e32 v5, v5, v11
	s_andn2_b64 vcc, exec, s[6:7]
	s_cbranch_vccnz .Lwt1_write
	v_mov_b32_e32 v8, v4
	v_ashrrev_i32_e32 v9, 31, v4
	v_lshl_add_u64 v[8:9], v[8:9], 2, s[28:29]
	global_load_dword v22, v[8:9], off
	global_load_dword v23, v[8:9], off offset:32
	global_load_dword v24, v[8:9], off offset:64
	global_load_dword v25, v[8:9], off offset:96
	global_load_dword v26, v[8:9], off offset:128
	global_load_dword v27, v[8:9], off offset:160
	global_load_dword v28, v[8:9], off offset:192
	global_load_dword v29, v[8:9], off offset:224
	s_waitcnt vmcnt(0)
	v_mul_f32_e32 v6, v6, v22
	v_mul_f32_e32 v13, v13, v23
	v_mul_f32_e32 v16, v16, v24
	v_mul_f32_e32 v17, v17, v25
	v_mul_f32_e32 v18, v18, v26
	v_mul_f32_e32 v19, v19, v27
	v_mul_f32_e32 v20, v20, v28
	v_mul_f32_e32 v21, v21, v29
.Lwt1_write:
	s_waitcnt vmcnt(0)
	s_barrier
	ds_write_b32 v5, v6
	ds_write_b32 v5, v13 offset:2080
	ds_write_b32 v5, v16 offset:4160
	ds_write_b32 v5, v17 offset:6240
	ds_write_b32 v5, v18 offset:8320
	ds_write_b32 v5, v19 offset:10400
	ds_write_b32 v5, v20 offset:12480
	ds_write_b32 v5, v21 offset:14560
	v_lshlrev_b32_e32 v2, 3, v10
	v_ashrrev_i32_e32 v12, 3, v10
	v_and_b32_e32 v6, 56, v2
	v_lshlrev_b32_e32 v2, 2, v12
	v_mul_u32_u24_e32 v3, 0x104, v6
	v_add3_u32 v8, 0, v2, v3
	s_waitcnt lgkmcnt(0)
	s_barrier
	ds_read2_b32 v[2:3], v8 offset1:65
	ds_read2_b32 v[4:5], v8 offset0:130 offset1:195
	v_add_u32_e32 v10, 0x400, v8
	ds_read2_b32 v[8:9], v10 offset0:4 offset1:69
	ds_read2_b32 v[10:11], v10 offset0:134 offset1:199
	s_add_u32 s0, s34, s24
	s_addc_u32 s1, s35, s5
	s_and_b32 s5, s26, 0x7fffffc0
	s_waitcnt lgkmcnt(3)
	v_cvt_pk_bf16_f32 v2, v2, v3
	s_waitcnt lgkmcnt(2)
	v_cvt_pk_bf16_f32 v3, v4, v5
	s_waitcnt lgkmcnt(1)
	v_cvt_pk_bf16_f32 v4, v8, v9
	v_add_u32_e32 v8, s5, v12
	v_ashrrev_i32_e32 v9, 31, v8
	v_lshlrev_b64 v[8:9], 11, v[8:9]
	v_lshl_add_u64 v[8:9], s[0:1], 0, v[8:9]
	s_lshl_b32 s16, s25, 1
	s_waitcnt lgkmcnt(0)
	v_cvt_pk_bf16_f32 v5, v10, v11
	v_lshl_add_u64 v[8:9], v[8:9], 0, s[16:17]

; __device__ __forceinline__ void wtile(LAS float* tile, const float* src, int lds_src, const float* gain, bf16_t* dst, int K, int n0, int k0, int c0, int nvalid) {
;     ...
;     for (int i = 0; i < 8; ++i) {
;         const int kk = (tid >> 6) + 8 * i, c = tid & 63;
;         float v = 0.f;
;         if (c0 + c < nvalid) { v = src[(size_t)(k0 + kk) * lds_src + c0 + c]; if (gain) v *= gain[k0 + kk]; }
;         tile[kk * 65 + c] = v;
;     }
; __device__ __forceinline__ void phase_weights(LAS unsigned char* lds, const Params& P) {
;     ...
;         if (r < T_IN) { const int nb = r / 16, kb = r % 16;
;             wtile(tile, P.in[3] + (size_t)l * DM * DIN, DIN, P.in[2] + l * DM, (bf16_t*)(ws + WS_WIN) + (size_t)l * DINP * DM, DM, nb * 64, kb * 64, nb * 64, DIN);
.LBB0_49:
	s_andn2_b64 vcc, exec, s[0:1]
	s_cbranch_vccnz .LBB0_22
	s_bfe_u32 s0, s4, 0x4001b
	s_add_i32 s0, s4, s0
	s_sext_i32_i16 s5, s0
	s_and_b32 s0, s0, 0xfff0
	s_sub_i32 s0, s4, s0
	s_mul_i32 s1, s18, 0xdb0000
	s_sext_i32_i16 s4, s0
	s_mul_hi_i32 s0, s18, 0xdb0000
	s_add_u32 s16, s54, s1
	s_addc_u32 s19, s55, s0
	s_lshl_b32 s0, s18, 10
	s_ashr_i32 s1, s0, 31
	s_lshl_b64 s[0:1], s[0:1], 2
	s_add_u32 s28, s52, s0
	s_addc_u32 s29, s53, s1
	s_lshl_b32 s0, s5, 2
	s_and_b32 s26, s0, 0xffffffc0
	s_ashr_i32 s27, s26, 31
	s_lshl_b32 s24, s4, 6
	v_mov_b32_e32 v10, v203
	s_lshl_b64 s[4:5], s[26:27], 2
	s_add_u32 s4, s16, s4
	v_and_b32_e32 v3, 63, v10
	v_bfi_b32 v4, 63, v10, s0
	s_addc_u32 s5, s19, s5
	v_lshlrev_b32_e32 v6, 2, v3
	v_cmp_gt_i32_e64 s[0:1], s43, v4
	v_lshl_add_u64 v[4:5], s[4:5], 0, v[6:7]
	v_cndmask_b32_e64 v6, 0, 1, s[12:13]
	v_ashrrev_i32_e32 v2, 6, v10
	v_mov_b32_e32 v11, 0
	v_cmp_ne_u32_e64 s[4:5], 1, v6
	v_mov_b32_e32 v12, 0
	v_mov_b32_e32 v16, 0
	v_mov_b32_e32 v17, 0
	v_mov_b32_e32 v18, 0
	v_mov_b32_e32 v19, 0
	v_mov_b32_e32 v20, 0
	v_mov_b32_e32 v21, 0
	v_lshl_add_u32 v3, v3, 2, 0
	v_mul_lo_u32 v6, v2, s40
	v_add_u32_e32 v6, v3, v6
	v_add_u32_e32 v8, s24, v2
	s_and_saveexec_b64 s[30:31], s[0:1]
	s_cbranch_execz .Lwt2_write
	v_mad_i64_i32 v[14:15], s[46:47], v8, s44, v[4:5]
	global_load_dword v12, v[14:15], off
	v_add_u32_e32 v3, 8, v8
	v_mad_i64_i32 v[24:25], s[46:47], v3, s44, v[4:5]
	global_load_dword v11, v[24:25], off
	v_add_u32_e32 v3, 16, v8
	v_mad_i64_i32 v[14:15], s[46:47], v3, s44, v[4:5]
	global_load_dword v16, v[14:15], off
	v_add_u32_e32 v3, 24, v8
	v_mad_i64_i32 v[24:25], s[46:47], v3, s44, v[4:5]
	global_load_dword v17, v[24:25], off
	v_add_u32_e32 v3, 32, v8
	v_mad_i64_i32 v[14:15], s[46:47], v3, s44, v[4:5]
	global_load_dword v18, v[14:15], off
	v_add_u32_e32 v3, 40, v8
	v_mad_i64_i32 v[24:25], s[46:47], v3, s44, v[4:5]
	global_load_dword v19, v[24:25], off
	v_add_u32_e32 v3, 48, v8
	v_mad_i64_i32 v[14:15], s[46:47], v3, s44, v[4:5]
	global_load_dword v20, v[14:15], off
	v_add_u32_e32 v3, 56, v8
	v_mad_i64_i32 v[24:25], s[46:47], v3, s44, v[4:5]
	global_load_dword v21, v[24:25], off
	s_and_b64 vcc, exec, s[4:5]
	s_cbranch_vccnz .Lwt2_write
	v_ashrrev_i32_e32 v9, 31, v8
	v_lshl_add_u64 v[8:9], v[8:9], 2, s[28:29]
	global_load_dword v22, v[8:9], off
	global_load_dword v23, v[8:9], off offset:32
	global_load_dword v24, v[8:9], off offset:64
	global_load_dword v25, v[8:9], off offset:96
	global_load_dword v26, v[8:9], off offset:128
	global_load_dword v27, v[8:9], off offset:160
	global_load_dword v28, v[8:9], off offset:192
	global_load_dword v29, v[8:9], off offset:224
	s_waitcnt vmcnt(0)
	v_mul_f32_e32 v12, v12, v22
	v_mul_f32_e32 v11, v11, v23
	v_mul_f32_e32 v16, v16, v24
	v_mul_f32_e32 v17, v17, v25
	v_mul_f32_e32 v18, v18, v26
	v_mul_f32_e32 v19, v19, v27
	v_mul_f32_e32 v20, v20, v28
	v_mul_f32_e32 v21, v21, v29
.Lwt2_write:
	s_or_b64 exec, exec, s[30:31]
	s_waitcnt vmcnt(0)
	s_barrier
	ds_write_b32 v6, v12
	ds_write_b32 v6, v11 offset:2080
	ds_write_b32 v6, v16 offset:4160
	ds_write_b32 v6, v17 offset:6240
	ds_write_b32 v6, v18 offset:8320
	ds_write_b32 v6, v19 offset:10400
	ds_write_b32 v6, v20 offset:12480
	v_mov_b32_e32 v8, v21
	s_branch .LBB0_21
